# phase-0 weight conversion rewritten LDS-free: one wave per 64 rows x 256 k, 64 loads in flight, 16-byte bf16 stores
# speedup vs baseline: 1.0343x; 1.0129x over previous
; #define LAS __attribute__((address_space(3)))
; __device__ __forceinline__ unsigned pk2(float lo, float hi) { unsigned r; asm volatile("v_cvt_pk_bf16_f32 %0, %1, %2" : "=v"(r) : "v"(lo), "v"(hi)); return r; }
; __device__ __forceinline__ const float* argf(int i) { return (const float*)kargs()[i]; }
; __device__ __forceinline__ int colmap(int mode, int n) {
;     if (mode == 0) return n < INW ? n : -1;
;     if (mode == 2) return ((n >> 7) & 1) * DFF + (n >> 8) * 128 + (n & 127);
;     return n;
; }
; __device__ __forceinline__ void transpose_tile(const float* src, int Nsrc, bf16_t* dst, int K, int n0, int k0, int mode, LAS float* scr, int tid) {
;     const int c = tid & 63, r0 = tid >> 6;
;     const int sc = colmap(mode, n0 + c);
; #pragma unroll
;     for (int i = 0; i < 8; ++i) { const int r = r0 + 8 * i; scr[r * 65 + c] = sc >= 0 ? src[(size_t)(k0 + r) * Nsrc + sc] : 0.f; }
;     __syncthreads();
;     const int kp = (tid & 31) * 2;
; #pragma unroll
;     for (int i = 0; i < 4; ++i) { const int r = (tid >> 5) + 16 * i;
;         *(unsigned*)(dst + (size_t)(n0 + r) * K + k0 + kp) = pk2(scr[kp * 65 + r], scr[(kp + 1) * 65 + r]); }
; __global__ void __launch_bounds__(512, 2) fwd_megakernel(Args a_unused) {
;     ...
;       for (int it = bid; it < 2 * I_L; it += G) {
;           const int l = it / I_L; int r = it % I_L;
;           if (r < I_IN) { transpose_tile(argf(5) + (size_t)l * D * INW, INW, (bf16_t*)(ws + WS_WIN) + (size_t)l * INP * D, D, (r / 16) * 64, (r % 16) * 64, 0, ldsf, tid); continue; } r -= I_IN;
;           if (r < I_OUT) { transpose_tile(argf(23) + (size_t)l * D * D, D, (bf16_t*)(ws + WS_WOUT) + (size_t)l * D * D, D, (r / 16) * 64, (r % 16) * 64, 1, ldsf, tid); continue; } r -= I_OUT;
;           if (r < I_UP) { transpose_tile(argf(26) + (size_t)l * D * NUP, NUP, (bf16_t*)(ws + WS_WUP) + (size_t)l * NUP * D, D, (r / 16) * 64, (r % 16) * 64, 2, ldsf, tid); continue; } r -= I_UP;
;           transpose_tile(argf(27) + (size_t)l * DFF * D, D, (bf16_t*)(ws + WS_WDN) + (size_t)l * D * DFF, DFF, (r / 44) * 64, (r % 44) * 64, 1, ldsf, tid);
.LBB0_6:
	s_mov_b32 s2, 0
	s_and_b32 s67, s58, 0xffffffc0
	v_mbcnt_lo_u32_b32 v2, -1, s2
	v_mbcnt_hi_u32_b32 v2, -1, v2
	s_mov_b32 s2, s68
	s_mov_b32 s3, s56
	v_add_u32_e32 v104, s67, v2
	s_mov_b64 s[4:5], s[0:1]
	s_cmp_eq_u32 s3, 0x100
	s_cbranch_scc0 .Ltr_orig
	s_lshr_b32 s10, s58, 6
	s_lshl_b32 s10, s10, 8
	s_add_i32 s10, s10, s2
	s_cmpk_lt_u32 s10, 0x660
	s_cbranch_scc0 .Ltr_done
	s_cmpk_lt_u32 s10, 0x330
	s_cselect_b32 s11, 0, 1
	s_mul_i32 s12, s11, 0x330
	s_sub_i32 s10, s10, s12
	s_load_dwordx2 s[14:15], s[0:1], 0xf8
	v_mbcnt_lo_u32_b32 v2, -1, 0
	v_mbcnt_hi_u32_b32 v2, -1, v2
	v_mov_b32_e32 v9, -1
	s_cmpk_lt_u32 s10, 0xe0
	s_cbranch_scc1 .Ltr_t0
	s_cmpk_lt_u32 s10, 0x120
	s_cbranch_scc1 .Ltr_t1
	s_cmpk_lt_u32 s10, 0x280
	s_cbranch_scc1 .Ltr_t2
	s_sub_i32 s10, s10, 0x280
	s_mul_i32 s13, s10, 0x1746
	s_lshr_b32 s13, s13, 16
	s_mul_i32 s16, s13, 11
	s_sub_i32 s16, s10, s16
	s_load_dwordx2 s[18:19], s[0:1], 0xd8
	s_mul_i32 s20, s11, 0xb00000
	s_movk_i32 s21, 0x1000
	s_mul_i32 s22, s11, 0x580000
	s_add_u32 s22, s22, 0x2800000
	s_movk_i32 s23, 0x1600
	s_lshl_b32 s24, s13, 6
	v_add_u32_e32 v3, s24, v2
	v_mov_b32_e32 v4, v3
	s_branch .Ltr_go
.Ltr_t0:
	s_lshr_b32 s13, s10, 2
	s_and_b32 s16, s10, 3
	s_load_dwordx2 s[18:19], s[0:1], 0x28
	s_mul_i32 s20, s11, 0xd14000
	s_movk_i32 s21, 0x3450
	s_mul_i32 s22, s11, 0x700000
	s_movk_i32 s23, 0x800
	s_lshl_b32 s24, s13, 6
	v_add_u32_e32 v3, s24, v2
	v_mov_b32_e32 v5, 0xd14
	v_cmp_gt_u32_e64 s[26:27], v5, v3
	s_nop 1
	v_cndmask_b32_e64 v4, 0, v3, s[26:27]
	v_cndmask_b32_e64 v9, 0, -1, s[26:27]
	s_branch .Ltr_go
.Ltr_t1:
	s_sub_i32 s10, s10, 0xe0
	s_lshr_b32 s13, s10, 2
	s_and_b32 s16, s10, 3
	s_load_dwordx2 s[18:19], s[0:1], 0xb8
	s_mul_i32 s20, s11, 0x400000
	s_movk_i32 s21, 0x1000
	s_mul_i32 s22, s11, 0x200000
	s_add_u32 s22, s22, 0xe00000
	s_movk_i32 s23, 0x800
	s_lshl_b32 s24, s13, 6
	v_add_u32_e32 v3, s24, v2
	v_mov_b32_e32 v4, v3
	s_branch .Ltr_go
.Ltr_t2:
	s_sub_i32 s10, s10, 0x120
	s_lshr_b32 s13, s10, 2
	s_and_b32 s16, s10, 3
	s_load_dwordx2 s[18:19], s[0:1], 0xd0
	s_mul_i32 s20, s11, 0x1600000
	s_movk_i32 s21, 0x5800
	s_mul_i32 s22, s11, 0xb00000
	s_add_u32 s22, s22, 0x1200000
	s_movk_i32 s23, 0x800
	s_lshl_b32 s24, s13, 6
	v_add_u32_e32 v3, s24, v2
	v_bfe_u32 v5, v3, 7, 1
	v_mul_u32_u24_e32 v5, 0xb00, v5
	v_lshrrev_b32_e32 v6, 8, v3
	v_lshl_add_u32 v5, v6, 7, v5
	v_and_b32_e32 v6, 0x7f, v3
	v_add_u32_e32 v4, v5, v6
.Ltr_go:
	v_lshlrev_b32_e32 v4, 2, v4
	v_mul_lo_u32 v3, v3, s23
	s_lshl_b32 s25, s16, 8
	s_mul_i32 s26, s25, s21
	s_add_u32 s20, s20, s26
	s_lshl_b32 s25, s25, 1
	s_add_u32 s22, s22, s25
	s_waitcnt lgkmcnt(0)
	s_add_u32 s18, s18, s20
	s_addc_u32 s19, s19, 0
	s_add_u32 s14, s14, s22
	s_addc_u32 s15, s15, 0
	s_nop 1
	global_load_dword v10, v4, s[18:19]
	s_add_u32 s18, s18, s21
	s_addc_u32 s19, s19, 0
	global_load_dword v11, v4, s[18:19]
	s_add_u32 s18, s18, s21
	s_addc_u32 s19, s19, 0
	global_load_dword v12, v4, s[18:19]
	s_add_u32 s18, s18, s21
	s_addc_u32 s19, s19, 0
	global_load_dword v13, v4, s[18:19]
	s_add_u32 s18, s18, s21
	s_addc_u32 s19, s19, 0
	global_load_dword v14, v4, s[18:19]
	s_add_u32 s18, s18, s21
	s_addc_u32 s19, s19, 0
	global_load_dword v15, v4, s[18:19]
	s_add_u32 s18, s18, s21
	s_addc_u32 s19, s19, 0
	global_load_dword v16, v4, s[18:19]
	s_add_u32 s18, s18, s21
	s_addc_u32 s19, s19, 0
	global_load_dword v17, v4, s[18:19]
	s_add_u32 s18, s18, s21
	s_addc_u32 s19, s19, 0
	global_load_dword v18, v4, s[18:19]
	s_add_u32 s18, s18, s21
	s_addc_u32 s19, s19, 0
	global_load_dword v19, v4, s[18:19]
	s_add_u32 s18, s18, s21
	s_addc_u32 s19, s19, 0
	global_load_dword v20, v4, s[18:19]
	s_add_u32 s18, s18, s21
	s_addc_u32 s19, s19, 0
	global_load_dword v21, v4, s[18:19]
	s_add_u32 s18, s18, s21
	s_addc_u32 s19, s19, 0
	global_load_dword v22, v4, s[18:19]
	s_add_u32 s18, s18, s21
	s_addc_u32 s19, s19, 0
	global_load_dword v23, v4, s[18:19]
	s_add_u32 s18, s18, s21
	s_addc_u32 s19, s19, 0
	global_load_dword v24, v4, s[18:19]
	s_add_u32 s18, s18, s21
	s_addc_u32 s19, s19, 0
	global_load_dword v25, v4, s[18:19]
	s_add_u32 s18, s18, s21
	s_addc_u32 s19, s19, 0
	global_load_dword v26, v4, s[18:19]
	s_add_u32 s18, s18, s21
	s_addc_u32 s19, s19, 0
	global_load_dword v27, v4, s[18:19]
	s_add_u32 s18, s18, s21
	s_addc_u32 s19, s19, 0
	global_load_dword v28, v4, s[18:19]
	s_add_u32 s18, s18, s21
	s_addc_u32 s19, s19, 0
	global_load_dword v29, v4, s[18:19]
	s_add_u32 s18, s18, s21
	s_addc_u32 s19, s19, 0
	global_load_dword v30, v4, s[18:19]
	s_add_u32 s18, s18, s21
	s_addc_u32 s19, s19, 0
	global_load_dword v31, v4, s[18:19]
	s_add_u32 s18, s18, s21
	s_addc_u32 s19, s19, 0
	global_load_dword v32, v4, s[18:19]
	s_add_u32 s18, s18, s21
	s_addc_u32 s19, s19, 0
	global_load_dword v33, v4, s[18:19]
	s_add_u32 s18, s18, s21
	s_addc_u32 s19, s19, 0
	global_load_dword v34, v4, s[18:19]
	s_add_u32 s18, s18, s21
	s_addc_u32 s19, s19, 0
	global_load_dword v35, v4, s[18:19]
	s_add_u32 s18, s18, s21
	s_addc_u32 s19, s19, 0
	global_load_dword v36, v4, s[18:19]
	s_add_u32 s18, s18, s21
	s_addc_u32 s19, s19, 0
	global_load_dword v37, v4, s[18:19]
	s_add_u32 s18, s18, s21
	s_addc_u32 s19, s19, 0
	global_load_dword v38, v4, s[18:19]
	s_add_u32 s18, s18, s21
	s_addc_u32 s19, s19, 0
	global_load_dword v39, v4, s[18:19]
	s_add_u32 s18, s18, s21
	s_addc_u32 s19, s19, 0
	global_load_dword v40, v4, s[18:19]
	s_add_u32 s18, s18, s21
	s_addc_u32 s19, s19, 0
	global_load_dword v41, v4, s[18:19]
	s_add_u32 s18, s18, s21
	s_addc_u32 s19, s19, 0
	global_load_dword v42, v4, s[18:19]
	s_add_u32 s18, s18, s21
	s_addc_u32 s19, s19, 0
	global_load_dword v43, v4, s[18:19]
	s_add_u32 s18, s18, s21
	s_addc_u32 s19, s19, 0
; #define LAS __attribute__((address_space(3)))
; __device__ __forceinline__ unsigned pk2(float lo, float hi) { unsigned r; asm volatile("v_cvt_pk_bf16_f32 %0, %1, %2" : "=v"(r) : "v"(lo), "v"(hi)); return r; }
; __device__ __forceinline__ void transpose_tile(const float* src, int Nsrc, bf16_t* dst, int K, int n0, int k0, int mode, LAS float* scr, int tid) {
;     const int c = tid & 63, r0 = tid >> 6;
;     const int sc = colmap(mode, n0 + c);
; #pragma unroll
;     for (int i = 0; i < 8; ++i) { const int r = r0 + 8 * i; scr[r * 65 + c] = sc >= 0 ? src[(size_t)(k0 + r) * Nsrc + sc] : 0.f; }
;     __syncthreads();
;     const int kp = (tid & 31) * 2;
; #pragma unroll
;     for (int i = 0; i < 4; ++i) { const int r = (tid >> 5) + 16 * i;
;         *(unsigned*)(dst + (size_t)(n0 + r) * K + k0 + kp) = pk2(scr[kp * 65 + r], scr[(kp + 1) * 65 + r]); }
	global_load_dword v44, v4, s[18:19]
	s_add_u32 s18, s18, s21
	s_addc_u32 s19, s19, 0
	global_load_dword v45, v4, s[18:19]
	s_add_u32 s18, s18, s21
	s_addc_u32 s19, s19, 0
	global_load_dword v46, v4, s[18:19]
	s_add_u32 s18, s18, s21
	s_addc_u32 s19, s19, 0
	global_load_dword v47, v4, s[18:19]
	s_add_u32 s18, s18, s21
	s_addc_u32 s19, s19, 0
	global_load_dword v48, v4, s[18:19]
	s_add_u32 s18, s18, s21
	s_addc_u32 s19, s19, 0
	global_load_dword v49, v4, s[18:19]
	s_add_u32 s18, s18, s21
	s_addc_u32 s19, s19, 0
	global_load_dword v50, v4, s[18:19]
	s_add_u32 s18, s18, s21
	s_addc_u32 s19, s19, 0
	global_load_dword v51, v4, s[18:19]
	s_add_u32 s18, s18, s21
	s_addc_u32 s19, s19, 0
	global_load_dword v52, v4, s[18:19]
	s_add_u32 s18, s18, s21
	s_addc_u32 s19, s19, 0
	global_load_dword v53, v4, s[18:19]
	s_add_u32 s18, s18, s21
	s_addc_u32 s19, s19, 0
	global_load_dword v54, v4, s[18:19]
	s_add_u32 s18, s18, s21
	s_addc_u32 s19, s19, 0
	global_load_dword v55, v4, s[18:19]
	s_add_u32 s18, s18, s21
	s_addc_u32 s19, s19, 0
	global_load_dword v56, v4, s[18:19]
	s_add_u32 s18, s18, s21
	s_addc_u32 s19, s19, 0
	global_load_dword v57, v4, s[18:19]
	s_add_u32 s18, s18, s21
	s_addc_u32 s19, s19, 0
	global_load_dword v58, v4, s[18:19]
	s_add_u32 s18, s18, s21
	s_addc_u32 s19, s19, 0
	global_load_dword v59, v4, s[18:19]
	s_add_u32 s18, s18, s21
	s_addc_u32 s19, s19, 0
	global_load_dword v60, v4, s[18:19]
	s_add_u32 s18, s18, s21
	s_addc_u32 s19, s19, 0
	global_load_dword v61, v4, s[18:19]
	s_add_u32 s18, s18, s21
	s_addc_u32 s19, s19, 0
	global_load_dword v62, v4, s[18:19]
	s_add_u32 s18, s18, s21
	s_addc_u32 s19, s19, 0
	global_load_dword v63, v4, s[18:19]
	s_add_u32 s18, s18, s21
	s_addc_u32 s19, s19, 0
	global_load_dword v64, v4, s[18:19]
	s_add_u32 s18, s18, s21
	s_addc_u32 s19, s19, 0
	global_load_dword v65, v4, s[18:19]
	s_add_u32 s18, s18, s21
	s_addc_u32 s19, s19, 0
	global_load_dword v66, v4, s[18:19]
	s_add_u32 s18, s18, s21
	s_addc_u32 s19, s19, 0
	global_load_dword v67, v4, s[18:19]
	s_add_u32 s18, s18, s21
	s_addc_u32 s19, s19, 0
	global_load_dword v68, v4, s[18:19]
	s_add_u32 s18, s18, s21
	s_addc_u32 s19, s19, 0
	global_load_dword v69, v4, s[18:19]
	s_add_u32 s18, s18, s21
	s_addc_u32 s19, s19, 0
	global_load_dword v70, v4, s[18:19]
	s_add_u32 s18, s18, s21
	s_addc_u32 s19, s19, 0
	global_load_dword v71, v4, s[18:19]
	s_add_u32 s18, s18, s21
	s_addc_u32 s19, s19, 0
	global_load_dword v72, v4, s[18:19]
	s_add_u32 s18, s18, s21
	s_addc_u32 s19, s19, 0
	global_load_dword v73, v4, s[18:19]
	s_add_u32 s18, s18, s21
	s_addc_u32 s19, s19, 0
	s_waitcnt vmcnt(32)
	v_cvt_pk_bf16_f32 v10, v10, v11
	v_cvt_pk_bf16_f32 v11, v12, v13
	v_cvt_pk_bf16_f32 v12, v14, v15
	v_cvt_pk_bf16_f32 v13, v16, v17
	v_and_b32_e32 v10, v10, v9
	v_and_b32_e32 v11, v11, v9
	v_and_b32_e32 v12, v12, v9
	v_and_b32_e32 v13, v13, v9
	global_store_dwordx4 v3, v[10:13], s[14:15]
	v_cvt_pk_bf16_f32 v18, v18, v19
	v_cvt_pk_bf16_f32 v19, v20, v21
	v_cvt_pk_bf16_f32 v20, v22, v23
	v_cvt_pk_bf16_f32 v21, v24, v25
	v_and_b32_e32 v18, v18, v9
	v_and_b32_e32 v19, v19, v9
	v_and_b32_e32 v20, v20, v9
	v_and_b32_e32 v21, v21, v9
	global_store_dwordx4 v3, v[18:21], s[14:15] offset:16
	v_cvt_pk_bf16_f32 v26, v26, v27
	v_cvt_pk_bf16_f32 v27, v28, v29
	v_cvt_pk_bf16_f32 v28, v30, v31
	v_cvt_pk_bf16_f32 v29, v32, v33
	v_and_b32_e32 v26, v26, v9
	v_and_b32_e32 v27, v27, v9
	v_and_b32_e32 v28, v28, v9
	v_and_b32_e32 v29, v29, v9
	global_store_dwordx4 v3, v[26:29], s[14:15] offset:32
	v_cvt_pk_bf16_f32 v34, v34, v35
	v_cvt_pk_bf16_f32 v35, v36, v37
	v_cvt_pk_bf16_f32 v36, v38, v39
	v_cvt_pk_bf16_f32 v37, v40, v41
	v_and_b32_e32 v34, v34, v9
	v_and_b32_e32 v35, v35, v9
	v_and_b32_e32 v36, v36, v9
	v_and_b32_e32 v37, v37, v9
	global_store_dwordx4 v3, v[34:37], s[14:15] offset:48
	s_add_u32 s14, s14, 64
	s_addc_u32 s15, s15, 0
	global_load_dword v10, v4, s[18:19]
	s_add_u32 s18, s18, s21
	s_addc_u32 s19, s19, 0
	global_load_dword v11, v4, s[18:19]
	s_add_u32 s18, s18, s21
	s_addc_u32 s19, s19, 0
	global_load_dword v12, v4, s[18:19]
	s_add_u32 s18, s18, s21
	s_addc_u32 s19, s19, 0
	global_load_dword v13, v4, s[18:19]
	s_add_u32 s18, s18, s21
	s_addc_u32 s19, s19, 0
	global_load_dword v14, v4, s[18:19]
	s_add_u32 s18, s18, s21
	s_addc_u32 s19, s19, 0
	global_load_dword v15, v4, s[18:19]
	s_add_u32 s18, s18, s21
	s_addc_u32 s19, s19, 0
	global_load_dword v16, v4, s[18:19]
	s_add_u32 s18, s18, s21
	s_addc_u32 s19, s19, 0
	global_load_dword v17, v4, s[18:19]
	s_add_u32 s18, s18, s21
	s_addc_u32 s19, s19, 0
	global_load_dword v18, v4, s[18:19]
	s_add_u32 s18, s18, s21
	s_addc_u32 s19, s19, 0
	global_load_dword v19, v4, s[18:19]
	s_add_u32 s18, s18, s21
	s_addc_u32 s19, s19, 0
	global_load_dword v20, v4, s[18:19]
	s_add_u32 s18, s18, s21
	s_addc_u32 s19, s19, 0
	global_load_dword v21, v4, s[18:19]
	s_add_u32 s18, s18, s21
	s_addc_u32 s19, s19, 0
	global_load_dword v22, v4, s[18:19]
	s_add_u32 s18, s18, s21
	s_addc_u32 s19, s19, 0
	global_load_dword v23, v4, s[18:19]
	s_add_u32 s18, s18, s21
	s_addc_u32 s19, s19, 0
	global_load_dword v24, v4, s[18:19]
	s_add_u32 s18, s18, s21
	s_addc_u32 s19, s19, 0
	global_load_dword v25, v4, s[18:19]
	s_add_u32 s18, s18, s21
	s_addc_u32 s19, s19, 0
	global_load_dword v26, v4, s[18:19]
	s_add_u32 s18, s18, s21
	s_addc_u32 s19, s19, 0
	global_load_dword v27, v4, s[18:19]
	s_add_u32 s18, s18, s21
	s_addc_u32 s19, s19, 0
	global_load_dword v28, v4, s[18:19]
	s_add_u32 s18, s18, s21
	s_addc_u32 s19, s19, 0
	global_load_dword v29, v4, s[18:19]
	s_add_u32 s18, s18, s21
	s_addc_u32 s19, s19, 0
	global_load_dword v30, v4, s[18:19]
	s_add_u32 s18, s18, s21
	s_addc_u32 s19, s19, 0
	global_load_dword v31, v4, s[18:19]
	s_add_u32 s18, s18, s21
	s_addc_u32 s19, s19, 0
	global_load_dword v32, v4, s[18:19]
	s_add_u32 s18, s18, s21
	s_addc_u32 s19, s19, 0
	global_load_dword v33, v4, s[18:19]
	s_add_u32 s18, s18, s21
	s_addc_u32 s19, s19, 0
	global_load_dword v34, v4, s[18:19]
	s_add_u32 s18, s18, s21
	s_addc_u32 s19, s19, 0
	global_load_dword v35, v4, s[18:19]
	s_add_u32 s18, s18, s21
	s_addc_u32 s19, s19, 0
	global_load_dword v36, v4, s[18:19]
	s_add_u32 s18, s18, s21
	s_addc_u32 s19, s19, 0
	global_load_dword v37, v4, s[18:19]
	s_add_u32 s18, s18, s21
	s_addc_u32 s19, s19, 0
	global_load_dword v38, v4, s[18:19]
	s_add_u32 s18, s18, s21
	s_addc_u32 s19, s19, 0
	global_load_dword v39, v4, s[18:19]
	s_add_u32 s18, s18, s21
	s_addc_u32 s19, s19, 0
	global_load_dword v40, v4, s[18:19]
	s_add_u32 s18, s18, s21
	s_addc_u32 s19, s19, 0
	global_load_dword v41, v4, s[18:19]
	s_add_u32 s18, s18, s21
	s_addc_u32 s19, s19, 0
	s_waitcnt vmcnt(36)
; #define LAS __attribute__((address_space(3)))
; __device__ __forceinline__ unsigned pk2(float lo, float hi) { unsigned r; asm volatile("v_cvt_pk_bf16_f32 %0, %1, %2" : "=v"(r) : "v"(lo), "v"(hi)); return r; }
; __device__ __forceinline__ void transpose_tile(const float* src, int Nsrc, bf16_t* dst, int K, int n0, int k0, int mode, LAS float* scr, int tid) {
;     const int c = tid & 63, r0 = tid >> 6;
;     const int sc = colmap(mode, n0 + c);
; #pragma unroll
;     for (int i = 0; i < 8; ++i) { const int r = r0 + 8 * i; scr[r * 65 + c] = sc >= 0 ? src[(size_t)(k0 + r) * Nsrc + sc] : 0.f; }
;     __syncthreads();
;     const int kp = (tid & 31) * 2;
; #pragma unroll
;     for (int i = 0; i < 4; ++i) { const int r = (tid >> 5) + 16 * i;
;         *(unsigned*)(dst + (size_t)(n0 + r) * K + k0 + kp) = pk2(scr[kp * 65 + r], scr[(kp + 1) * 65 + r]); }
	v_cvt_pk_bf16_f32 v42, v42, v43
	v_cvt_pk_bf16_f32 v43, v44, v45
	v_cvt_pk_bf16_f32 v44, v46, v47
	v_cvt_pk_bf16_f32 v45, v48, v49
	v_and_b32_e32 v42, v42, v9
	v_and_b32_e32 v43, v43, v9
	v_and_b32_e32 v44, v44, v9
	v_and_b32_e32 v45, v45, v9
	global_store_dwordx4 v3, v[42:45], s[14:15]
	v_cvt_pk_bf16_f32 v50, v50, v51
	v_cvt_pk_bf16_f32 v51, v52, v53
	v_cvt_pk_bf16_f32 v52, v54, v55
	v_cvt_pk_bf16_f32 v53, v56, v57
	v_and_b32_e32 v50, v50, v9
	v_and_b32_e32 v51, v51, v9
	v_and_b32_e32 v52, v52, v9
	v_and_b32_e32 v53, v53, v9
	global_store_dwordx4 v3, v[50:53], s[14:15] offset:16
	v_cvt_pk_bf16_f32 v58, v58, v59
	v_cvt_pk_bf16_f32 v59, v60, v61
	v_cvt_pk_bf16_f32 v60, v62, v63
	v_cvt_pk_bf16_f32 v61, v64, v65
	v_and_b32_e32 v58, v58, v9
	v_and_b32_e32 v59, v59, v9
	v_and_b32_e32 v60, v60, v9
	v_and_b32_e32 v61, v61, v9
	global_store_dwordx4 v3, v[58:61], s[14:15] offset:32
	v_cvt_pk_bf16_f32 v66, v66, v67
	v_cvt_pk_bf16_f32 v67, v68, v69
	v_cvt_pk_bf16_f32 v68, v70, v71
	v_cvt_pk_bf16_f32 v69, v72, v73
	v_and_b32_e32 v66, v66, v9
	v_and_b32_e32 v67, v67, v9
	v_and_b32_e32 v68, v68, v9
	v_and_b32_e32 v69, v69, v9
	global_store_dwordx4 v3, v[66:69], s[14:15] offset:48
	s_add_u32 s14, s14, 64
	s_addc_u32 s15, s15, 0
	global_load_dword v42, v4, s[18:19]
	s_add_u32 s18, s18, s21
	s_addc_u32 s19, s19, 0
	global_load_dword v43, v4, s[18:19]
	s_add_u32 s18, s18, s21
	s_addc_u32 s19, s19, 0
	global_load_dword v44, v4, s[18:19]
	s_add_u32 s18, s18, s21
	s_addc_u32 s19, s19, 0
	global_load_dword v45, v4, s[18:19]
	s_add_u32 s18, s18, s21
	s_addc_u32 s19, s19, 0
	global_load_dword v46, v4, s[18:19]
	s_add_u32 s18, s18, s21
	s_addc_u32 s19, s19, 0
	global_load_dword v47, v4, s[18:19]
	s_add_u32 s18, s18, s21
	s_addc_u32 s19, s19, 0
	global_load_dword v48, v4, s[18:19]
	s_add_u32 s18, s18, s21
	s_addc_u32 s19, s19, 0
	global_load_dword v49, v4, s[18:19]
	s_add_u32 s18, s18, s21
	s_addc_u32 s19, s19, 0
	global_load_dword v50, v4, s[18:19]
	s_add_u32 s18, s18, s21
	s_addc_u32 s19, s19, 0
	global_load_dword v51, v4, s[18:19]
	s_add_u32 s18, s18, s21
	s_addc_u32 s19, s19, 0
	global_load_dword v52, v4, s[18:19]
	s_add_u32 s18, s18, s21
	s_addc_u32 s19, s19, 0
	global_load_dword v53, v4, s[18:19]
	s_add_u32 s18, s18, s21
	s_addc_u32 s19, s19, 0
	global_load_dword v54, v4, s[18:19]
	s_add_u32 s18, s18, s21
	s_addc_u32 s19, s19, 0
	global_load_dword v55, v4, s[18:19]
	s_add_u32 s18, s18, s21
	s_addc_u32 s19, s19, 0
	global_load_dword v56, v4, s[18:19]
	s_add_u32 s18, s18, s21
	s_addc_u32 s19, s19, 0
	global_load_dword v57, v4, s[18:19]
	s_add_u32 s18, s18, s21
	s_addc_u32 s19, s19, 0
	global_load_dword v58, v4, s[18:19]
	s_add_u32 s18, s18, s21
	s_addc_u32 s19, s19, 0
	global_load_dword v59, v4, s[18:19]
	s_add_u32 s18, s18, s21
	s_addc_u32 s19, s19, 0
	global_load_dword v60, v4, s[18:19]
	s_add_u32 s18, s18, s21
	s_addc_u32 s19, s19, 0
	global_load_dword v61, v4, s[18:19]
	s_add_u32 s18, s18, s21
	s_addc_u32 s19, s19, 0
	global_load_dword v62, v4, s[18:19]
	s_add_u32 s18, s18, s21
	s_addc_u32 s19, s19, 0
	global_load_dword v63, v4, s[18:19]
	s_add_u32 s18, s18, s21
	s_addc_u32 s19, s19, 0
	global_load_dword v64, v4, s[18:19]
	s_add_u32 s18, s18, s21
	s_addc_u32 s19, s19, 0
	global_load_dword v65, v4, s[18:19]
	s_add_u32 s18, s18, s21
	s_addc_u32 s19, s19, 0
	global_load_dword v66, v4, s[18:19]
	s_add_u32 s18, s18, s21
	s_addc_u32 s19, s19, 0
	global_load_dword v67, v4, s[18:19]
	s_add_u32 s18, s18, s21
	s_addc_u32 s19, s19, 0
	global_load_dword v68, v4, s[18:19]
	s_add_u32 s18, s18, s21
	s_addc_u32 s19, s19, 0
	global_load_dword v69, v4, s[18:19]
	s_add_u32 s18, s18, s21
	s_addc_u32 s19, s19, 0
	global_load_dword v70, v4, s[18:19]
	s_add_u32 s18, s18, s21
	s_addc_u32 s19, s19, 0
	global_load_dword v71, v4, s[18:19]
	s_add_u32 s18, s18, s21
	s_addc_u32 s19, s19, 0
	global_load_dword v72, v4, s[18:19]
	s_add_u32 s18, s18, s21
	s_addc_u32 s19, s19, 0
	global_load_dword v73, v4, s[18:19]
	s_add_u32 s18, s18, s21
	s_addc_u32 s19, s19, 0
	s_waitcnt vmcnt(36)
	v_cvt_pk_bf16_f32 v10, v10, v11
	v_cvt_pk_bf16_f32 v11, v12, v13
	v_cvt_pk_bf16_f32 v12, v14, v15
	v_cvt_pk_bf16_f32 v13, v16, v17
	v_and_b32_e32 v10, v10, v9
	v_and_b32_e32 v11, v11, v9
	v_and_b32_e32 v12, v12, v9
	v_and_b32_e32 v13, v13, v9
	global_store_dwordx4 v3, v[10:13], s[14:15]
	v_cvt_pk_bf16_f32 v18, v18, v19
	v_cvt_pk_bf16_f32 v19, v20, v21
	v_cvt_pk_bf16_f32 v20, v22, v23
	v_cvt_pk_bf16_f32 v21, v24, v25
	v_and_b32_e32 v18, v18, v9
	v_and_b32_e32 v19, v19, v9
	v_and_b32_e32 v20, v20, v9
	v_and_b32_e32 v21, v21, v9
	global_store_dwordx4 v3, v[18:21], s[14:15] offset:16
	v_cvt_pk_bf16_f32 v26, v26, v27
	v_cvt_pk_bf16_f32 v27, v28, v29
	v_cvt_pk_bf16_f32 v28, v30, v31
	v_cvt_pk_bf16_f32 v29, v32, v33
	v_and_b32_e32 v26, v26, v9
	v_and_b32_e32 v27, v27, v9
	v_and_b32_e32 v28, v28, v9
	v_and_b32_e32 v29, v29, v9
	global_store_dwordx4 v3, v[26:29], s[14:15] offset:32
	v_cvt_pk_bf16_f32 v34, v34, v35
	v_cvt_pk_bf16_f32 v35, v36, v37
	v_cvt_pk_bf16_f32 v36, v38, v39
	v_cvt_pk_bf16_f32 v37, v40, v41
	v_and_b32_e32 v34, v34, v9
	v_and_b32_e32 v35, v35, v9
	v_and_b32_e32 v36, v36, v9
	v_and_b32_e32 v37, v37, v9
	global_store_dwordx4 v3, v[34:37], s[14:15] offset:48
	s_add_u32 s14, s14, 64
	s_addc_u32 s15, s15, 0
	global_load_dword v10, v4, s[18:19]
	s_add_u32 s18, s18, s21
	s_addc_u32 s19, s19, 0
	global_load_dword v11, v4, s[18:19]
	s_add_u32 s18, s18, s21
	s_addc_u32 s19, s19, 0
	global_load_dword v12, v4, s[18:19]
	s_add_u32 s18, s18, s21
	s_addc_u32 s19, s19, 0
	global_load_dword v13, v4, s[18:19]
	s_add_u32 s18, s18, s21
	s_addc_u32 s19, s19, 0
	global_load_dword v14, v4, s[18:19]
	s_add_u32 s18, s18, s21
; #define LAS __attribute__((address_space(3)))
; __device__ __forceinline__ unsigned pk2(float lo, float hi) { unsigned r; asm volatile("v_cvt_pk_bf16_f32 %0, %1, %2" : "=v"(r) : "v"(lo), "v"(hi)); return r; }
; __device__ __forceinline__ void transpose_tile(const float* src, int Nsrc, bf16_t* dst, int K, int n0, int k0, int mode, LAS float* scr, int tid) {
;     const int c = tid & 63, r0 = tid >> 6;
;     const int sc = colmap(mode, n0 + c);
; #pragma unroll
;     for (int i = 0; i < 8; ++i) { const int r = r0 + 8 * i; scr[r * 65 + c] = sc >= 0 ? src[(size_t)(k0 + r) * Nsrc + sc] : 0.f; }
;     __syncthreads();
;     const int kp = (tid & 31) * 2;
; #pragma unroll
;     for (int i = 0; i < 4; ++i) { const int r = (tid >> 5) + 16 * i;
;         *(unsigned*)(dst + (size_t)(n0 + r) * K + k0 + kp) = pk2(scr[kp * 65 + r], scr[(kp + 1) * 65 + r]); }
	s_addc_u32 s19, s19, 0
	global_load_dword v15, v4, s[18:19]
	s_add_u32 s18, s18, s21
	s_addc_u32 s19, s19, 0
	global_load_dword v16, v4, s[18:19]
	s_add_u32 s18, s18, s21
	s_addc_u32 s19, s19, 0
	global_load_dword v17, v4, s[18:19]
	s_add_u32 s18, s18, s21
	s_addc_u32 s19, s19, 0
	global_load_dword v18, v4, s[18:19]
	s_add_u32 s18, s18, s21
	s_addc_u32 s19, s19, 0
	global_load_dword v19, v4, s[18:19]
	s_add_u32 s18, s18, s21
	s_addc_u32 s19, s19, 0
	global_load_dword v20, v4, s[18:19]
	s_add_u32 s18, s18, s21
	s_addc_u32 s19, s19, 0
	global_load_dword v21, v4, s[18:19]
	s_add_u32 s18, s18, s21
	s_addc_u32 s19, s19, 0
	global_load_dword v22, v4, s[18:19]
	s_add_u32 s18, s18, s21
	s_addc_u32 s19, s19, 0
	global_load_dword v23, v4, s[18:19]
	s_add_u32 s18, s18, s21
	s_addc_u32 s19, s19, 0
	global_load_dword v24, v4, s[18:19]
	s_add_u32 s18, s18, s21
	s_addc_u32 s19, s19, 0
	global_load_dword v25, v4, s[18:19]
	s_add_u32 s18, s18, s21
	s_addc_u32 s19, s19, 0
	global_load_dword v26, v4, s[18:19]
	s_add_u32 s18, s18, s21
	s_addc_u32 s19, s19, 0
	global_load_dword v27, v4, s[18:19]
	s_add_u32 s18, s18, s21
	s_addc_u32 s19, s19, 0
	global_load_dword v28, v4, s[18:19]
	s_add_u32 s18, s18, s21
	s_addc_u32 s19, s19, 0
	global_load_dword v29, v4, s[18:19]
	s_add_u32 s18, s18, s21
	s_addc_u32 s19, s19, 0
	global_load_dword v30, v4, s[18:19]
	s_add_u32 s18, s18, s21
	s_addc_u32 s19, s19, 0
	global_load_dword v31, v4, s[18:19]
	s_add_u32 s18, s18, s21
	s_addc_u32 s19, s19, 0
	global_load_dword v32, v4, s[18:19]
	s_add_u32 s18, s18, s21
	s_addc_u32 s19, s19, 0
	global_load_dword v33, v4, s[18:19]
	s_add_u32 s18, s18, s21
	s_addc_u32 s19, s19, 0
	global_load_dword v34, v4, s[18:19]
	s_add_u32 s18, s18, s21
	s_addc_u32 s19, s19, 0
	global_load_dword v35, v4, s[18:19]
	s_add_u32 s18, s18, s21
	s_addc_u32 s19, s19, 0
	global_load_dword v36, v4, s[18:19]
	s_add_u32 s18, s18, s21
	s_addc_u32 s19, s19, 0
	global_load_dword v37, v4, s[18:19]
	s_add_u32 s18, s18, s21
	s_addc_u32 s19, s19, 0
	global_load_dword v38, v4, s[18:19]
	s_add_u32 s18, s18, s21
	s_addc_u32 s19, s19, 0
	global_load_dword v39, v4, s[18:19]
	s_add_u32 s18, s18, s21
	s_addc_u32 s19, s19, 0
	global_load_dword v40, v4, s[18:19]
	s_add_u32 s18, s18, s21
	s_addc_u32 s19, s19, 0
	global_load_dword v41, v4, s[18:19]
	s_add_u32 s18, s18, s21
	s_addc_u32 s19, s19, 0
	s_waitcnt vmcnt(36)
	v_cvt_pk_bf16_f32 v42, v42, v43
	v_cvt_pk_bf16_f32 v43, v44, v45
	v_cvt_pk_bf16_f32 v44, v46, v47
	v_cvt_pk_bf16_f32 v45, v48, v49
	v_and_b32_e32 v42, v42, v9
	v_and_b32_e32 v43, v43, v9
	v_and_b32_e32 v44, v44, v9
	v_and_b32_e32 v45, v45, v9
	global_store_dwordx4 v3, v[42:45], s[14:15]
	v_cvt_pk_bf16_f32 v50, v50, v51
	v_cvt_pk_bf16_f32 v51, v52, v53
	v_cvt_pk_bf16_f32 v52, v54, v55
	v_cvt_pk_bf16_f32 v53, v56, v57
	v_and_b32_e32 v50, v50, v9
	v_and_b32_e32 v51, v51, v9
	v_and_b32_e32 v52, v52, v9
	v_and_b32_e32 v53, v53, v9
	global_store_dwordx4 v3, v[50:53], s[14:15] offset:16
	v_cvt_pk_bf16_f32 v58, v58, v59
	v_cvt_pk_bf16_f32 v59, v60, v61
	v_cvt_pk_bf16_f32 v60, v62, v63
	v_cvt_pk_bf16_f32 v61, v64, v65
	v_and_b32_e32 v58, v58, v9
	v_and_b32_e32 v59, v59, v9
	v_and_b32_e32 v60, v60, v9
	v_and_b32_e32 v61, v61, v9
	global_store_dwordx4 v3, v[58:61], s[14:15] offset:32
	v_cvt_pk_bf16_f32 v66, v66, v67
	v_cvt_pk_bf16_f32 v67, v68, v69
	v_cvt_pk_bf16_f32 v68, v70, v71
	v_cvt_pk_bf16_f32 v69, v72, v73
	v_and_b32_e32 v66, v66, v9
	v_and_b32_e32 v67, v67, v9
	v_and_b32_e32 v68, v68, v9
	v_and_b32_e32 v69, v69, v9
	global_store_dwordx4 v3, v[66:69], s[14:15] offset:48
	s_add_u32 s14, s14, 64
	s_addc_u32 s15, s15, 0
	global_load_dword v42, v4, s[18:19]
	s_add_u32 s18, s18, s21
	s_addc_u32 s19, s19, 0
	global_load_dword v43, v4, s[18:19]
	s_add_u32 s18, s18, s21
	s_addc_u32 s19, s19, 0
	global_load_dword v44, v4, s[18:19]
	s_add_u32 s18, s18, s21
	s_addc_u32 s19, s19, 0
	global_load_dword v45, v4, s[18:19]
	s_add_u32 s18, s18, s21
	s_addc_u32 s19, s19, 0
	global_load_dword v46, v4, s[18:19]
	s_add_u32 s18, s18, s21
	s_addc_u32 s19, s19, 0
	global_load_dword v47, v4, s[18:19]
	s_add_u32 s18, s18, s21
	s_addc_u32 s19, s19, 0
	global_load_dword v48, v4, s[18:19]
	s_add_u32 s18, s18, s21
	s_addc_u32 s19, s19, 0
	global_load_dword v49, v4, s[18:19]
	s_add_u32 s18, s18, s21
	s_addc_u32 s19, s19, 0
	global_load_dword v50, v4, s[18:19]
	s_add_u32 s18, s18, s21
	s_addc_u32 s19, s19, 0
	global_load_dword v51, v4, s[18:19]
	s_add_u32 s18, s18, s21
	s_addc_u32 s19, s19, 0
	global_load_dword v52, v4, s[18:19]
	s_add_u32 s18, s18, s21
	s_addc_u32 s19, s19, 0
	global_load_dword v53, v4, s[18:19]
	s_add_u32 s18, s18, s21
	s_addc_u32 s19, s19, 0
	global_load_dword v54, v4, s[18:19]
	s_add_u32 s18, s18, s21
	s_addc_u32 s19, s19, 0
	global_load_dword v55, v4, s[18:19]
	s_add_u32 s18, s18, s21
	s_addc_u32 s19, s19, 0
	global_load_dword v56, v4, s[18:19]
	s_add_u32 s18, s18, s21
	s_addc_u32 s19, s19, 0
	global_load_dword v57, v4, s[18:19]
	s_add_u32 s18, s18, s21
	s_addc_u32 s19, s19, 0
	global_load_dword v58, v4, s[18:19]
	s_add_u32 s18, s18, s21
	s_addc_u32 s19, s19, 0
	global_load_dword v59, v4, s[18:19]
	s_add_u32 s18, s18, s21
	s_addc_u32 s19, s19, 0
	global_load_dword v60, v4, s[18:19]
	s_add_u32 s18, s18, s21
	s_addc_u32 s19, s19, 0
	global_load_dword v61, v4, s[18:19]
	s_add_u32 s18, s18, s21
	s_addc_u32 s19, s19, 0
	global_load_dword v62, v4, s[18:19]
	s_add_u32 s18, s18, s21
	s_addc_u32 s19, s19, 0
	global_load_dword v63, v4, s[18:19]
	s_add_u32 s18, s18, s21
	s_addc_u32 s19, s19, 0
	global_load_dword v64, v4, s[18:19]
	s_add_u32 s18, s18, s21
	s_addc_u32 s19, s19, 0
	global_load_dword v65, v4, s[18:19]
	s_add_u32 s18, s18, s21
	s_addc_u32 s19, s19, 0
	global_load_dword v66, v4, s[18:19]
	s_add_u32 s18, s18, s21
	s_addc_u32 s19, s19, 0
	global_load_dword v67, v4, s[18:19]
	s_add_u32 s18, s18, s21
	s_addc_u32 s19, s19, 0
	global_load_dword v68, v4, s[18:19]
	s_add_u32 s18, s18, s21
	s_addc_u32 s19, s19, 0
	global_load_dword v69, v4, s[18:19]
	s_add_u32 s18, s18, s21
	s_addc_u32 s19, s19, 0
	global_load_dword v70, v4, s[18:19]
	s_add_u32 s18, s18, s21
	s_addc_u32 s19, s19, 0
	global_load_dword v71, v4, s[18:19]
	s_add_u32 s18, s18, s21
	s_addc_u32 s19, s19, 0
	global_load_dword v72, v4, s[18:19]
	s_add_u32 s18, s18, s21
	s_addc_u32 s19, s19, 0
	global_load_dword v73, v4, s[18:19]
	s_add_u32 s18, s18, s21
	s_addc_u32 s19, s19, 0
	s_waitcnt vmcnt(36)
; #define LAS __attribute__((address_space(3)))
; __device__ __forceinline__ unsigned pk2(float lo, float hi) { unsigned r; asm volatile("v_cvt_pk_bf16_f32 %0, %1, %2" : "=v"(r) : "v"(lo), "v"(hi)); return r; }
; __device__ __forceinline__ void transpose_tile(const float* src, int Nsrc, bf16_t* dst, int K, int n0, int k0, int mode, LAS float* scr, int tid) {
;     const int c = tid & 63, r0 = tid >> 6;
;     const int sc = colmap(mode, n0 + c);
; #pragma unroll
;     for (int i = 0; i < 8; ++i) { const int r = r0 + 8 * i; scr[r * 65 + c] = sc >= 0 ? src[(size_t)(k0 + r) * Nsrc + sc] : 0.f; }
;     __syncthreads();
;     const int kp = (tid & 31) * 2;
; #pragma unroll
;     for (int i = 0; i < 4; ++i) { const int r = (tid >> 5) + 16 * i;
;         *(unsigned*)(dst + (size_t)(n0 + r) * K + k0 + kp) = pk2(scr[kp * 65 + r], scr[(kp + 1) * 65 + r]); }
	v_cvt_pk_bf16_f32 v10, v10, v11
	v_cvt_pk_bf16_f32 v11, v12, v13
	v_cvt_pk_bf16_f32 v12, v14, v15
	v_cvt_pk_bf16_f32 v13, v16, v17
	v_and_b32_e32 v10, v10, v9
	v_and_b32_e32 v11, v11, v9
	v_and_b32_e32 v12, v12, v9
	v_and_b32_e32 v13, v13, v9
	global_store_dwordx4 v3, v[10:13], s[14:15]
	v_cvt_pk_bf16_f32 v18, v18, v19
	v_cvt_pk_bf16_f32 v19, v20, v21
	v_cvt_pk_bf16_f32 v20, v22, v23
	v_cvt_pk_bf16_f32 v21, v24, v25
	v_and_b32_e32 v18, v18, v9
	v_and_b32_e32 v19, v19, v9
	v_and_b32_e32 v20, v20, v9
	v_and_b32_e32 v21, v21, v9
	global_store_dwordx4 v3, v[18:21], s[14:15] offset:16
	v_cvt_pk_bf16_f32 v26, v26, v27
	v_cvt_pk_bf16_f32 v27, v28, v29
	v_cvt_pk_bf16_f32 v28, v30, v31
	v_cvt_pk_bf16_f32 v29, v32, v33
	v_and_b32_e32 v26, v26, v9
	v_and_b32_e32 v27, v27, v9
	v_and_b32_e32 v28, v28, v9
	v_and_b32_e32 v29, v29, v9
	global_store_dwordx4 v3, v[26:29], s[14:15] offset:32
	v_cvt_pk_bf16_f32 v34, v34, v35
	v_cvt_pk_bf16_f32 v35, v36, v37
	v_cvt_pk_bf16_f32 v36, v38, v39
	v_cvt_pk_bf16_f32 v37, v40, v41
	v_and_b32_e32 v34, v34, v9
	v_and_b32_e32 v35, v35, v9
	v_and_b32_e32 v36, v36, v9
	v_and_b32_e32 v37, v37, v9
	global_store_dwordx4 v3, v[34:37], s[14:15] offset:48
	s_add_u32 s14, s14, 64
	s_addc_u32 s15, s15, 0
	global_load_dword v10, v4, s[18:19]
	s_add_u32 s18, s18, s21
	s_addc_u32 s19, s19, 0
	global_load_dword v11, v4, s[18:19]
	s_add_u32 s18, s18, s21
	s_addc_u32 s19, s19, 0
	global_load_dword v12, v4, s[18:19]
	s_add_u32 s18, s18, s21
	s_addc_u32 s19, s19, 0
	global_load_dword v13, v4, s[18:19]
	s_add_u32 s18, s18, s21
	s_addc_u32 s19, s19, 0
	global_load_dword v14, v4, s[18:19]
	s_add_u32 s18, s18, s21
	s_addc_u32 s19, s19, 0
	global_load_dword v15, v4, s[18:19]
	s_add_u32 s18, s18, s21
	s_addc_u32 s19, s19, 0
	global_load_dword v16, v4, s[18:19]
	s_add_u32 s18, s18, s21
	s_addc_u32 s19, s19, 0
	global_load_dword v17, v4, s[18:19]
	s_add_u32 s18, s18, s21
	s_addc_u32 s19, s19, 0
	global_load_dword v18, v4, s[18:19]
	s_add_u32 s18, s18, s21
	s_addc_u32 s19, s19, 0
	global_load_dword v19, v4, s[18:19]
	s_add_u32 s18, s18, s21
	s_addc_u32 s19, s19, 0
	global_load_dword v20, v4, s[18:19]
	s_add_u32 s18, s18, s21
	s_addc_u32 s19, s19, 0
	global_load_dword v21, v4, s[18:19]
	s_add_u32 s18, s18, s21
	s_addc_u32 s19, s19, 0
	global_load_dword v22, v4, s[18:19]
	s_add_u32 s18, s18, s21
	s_addc_u32 s19, s19, 0
	global_load_dword v23, v4, s[18:19]
	s_add_u32 s18, s18, s21
	s_addc_u32 s19, s19, 0
	global_load_dword v24, v4, s[18:19]
	s_add_u32 s18, s18, s21
	s_addc_u32 s19, s19, 0
	global_load_dword v25, v4, s[18:19]
	s_add_u32 s18, s18, s21
	s_addc_u32 s19, s19, 0
	global_load_dword v26, v4, s[18:19]
	s_add_u32 s18, s18, s21
	s_addc_u32 s19, s19, 0
	global_load_dword v27, v4, s[18:19]
	s_add_u32 s18, s18, s21
	s_addc_u32 s19, s19, 0
	global_load_dword v28, v4, s[18:19]
	s_add_u32 s18, s18, s21
	s_addc_u32 s19, s19, 0
	global_load_dword v29, v4, s[18:19]
	s_add_u32 s18, s18, s21
	s_addc_u32 s19, s19, 0
	global_load_dword v30, v4, s[18:19]
	s_add_u32 s18, s18, s21
	s_addc_u32 s19, s19, 0
	global_load_dword v31, v4, s[18:19]
	s_add_u32 s18, s18, s21
	s_addc_u32 s19, s19, 0
	global_load_dword v32, v4, s[18:19]
	s_add_u32 s18, s18, s21
	s_addc_u32 s19, s19, 0
	global_load_dword v33, v4, s[18:19]
	s_add_u32 s18, s18, s21
	s_addc_u32 s19, s19, 0
	global_load_dword v34, v4, s[18:19]
	s_add_u32 s18, s18, s21
	s_addc_u32 s19, s19, 0
	global_load_dword v35, v4, s[18:19]
	s_add_u32 s18, s18, s21
	s_addc_u32 s19, s19, 0
	global_load_dword v36, v4, s[18:19]
	s_add_u32 s18, s18, s21
	s_addc_u32 s19, s19, 0
	global_load_dword v37, v4, s[18:19]
	s_add_u32 s18, s18, s21
	s_addc_u32 s19, s19, 0
	global_load_dword v38, v4, s[18:19]
	s_add_u32 s18, s18, s21
	s_addc_u32 s19, s19, 0
	global_load_dword v39, v4, s[18:19]
	s_add_u32 s18, s18, s21
	s_addc_u32 s19, s19, 0
	global_load_dword v40, v4, s[18:19]
	s_add_u32 s18, s18, s21
	s_addc_u32 s19, s19, 0
	global_load_dword v41, v4, s[18:19]
	s_add_u32 s18, s18, s21
	s_addc_u32 s19, s19, 0
	s_waitcnt vmcnt(36)
	v_cvt_pk_bf16_f32 v42, v42, v43
	v_cvt_pk_bf16_f32 v43, v44, v45
	v_cvt_pk_bf16_f32 v44, v46, v47
	v_cvt_pk_bf16_f32 v45, v48, v49
	v_and_b32_e32 v42, v42, v9
	v_and_b32_e32 v43, v43, v9
	v_and_b32_e32 v44, v44, v9
	v_and_b32_e32 v45, v45, v9
	global_store_dwordx4 v3, v[42:45], s[14:15]
	v_cvt_pk_bf16_f32 v50, v50, v51
	v_cvt_pk_bf16_f32 v51, v52, v53
	v_cvt_pk_bf16_f32 v52, v54, v55
	v_cvt_pk_bf16_f32 v53, v56, v57
	v_and_b32_e32 v50, v50, v9
	v_and_b32_e32 v51, v51, v9
	v_and_b32_e32 v52, v52, v9
	v_and_b32_e32 v53, v53, v9
	global_store_dwordx4 v3, v[50:53], s[14:15] offset:16
	v_cvt_pk_bf16_f32 v58, v58, v59
	v_cvt_pk_bf16_f32 v59, v60, v61
	v_cvt_pk_bf16_f32 v60, v62, v63
	v_cvt_pk_bf16_f32 v61, v64, v65
	v_and_b32_e32 v58, v58, v9
	v_and_b32_e32 v59, v59, v9
	v_and_b32_e32 v60, v60, v9
	v_and_b32_e32 v61, v61, v9
	global_store_dwordx4 v3, v[58:61], s[14:15] offset:32
	v_cvt_pk_bf16_f32 v66, v66, v67
	v_cvt_pk_bf16_f32 v67, v68, v69
	v_cvt_pk_bf16_f32 v68, v70, v71
	v_cvt_pk_bf16_f32 v69, v72, v73
	v_and_b32_e32 v66, v66, v9
	v_and_b32_e32 v67, v67, v9
	v_and_b32_e32 v68, v68, v9
	v_and_b32_e32 v69, v69, v9
	global_store_dwordx4 v3, v[66:69], s[14:15] offset:48
	s_add_u32 s14, s14, 64
	s_addc_u32 s15, s15, 0
	global_load_dword v42, v4, s[18:19]
	s_add_u32 s18, s18, s21
	s_addc_u32 s19, s19, 0
	global_load_dword v43, v4, s[18:19]
	s_add_u32 s18, s18, s21
	s_addc_u32 s19, s19, 0
	global_load_dword v44, v4, s[18:19]
	s_add_u32 s18, s18, s21
	s_addc_u32 s19, s19, 0
	global_load_dword v45, v4, s[18:19]
	s_add_u32 s18, s18, s21
	s_addc_u32 s19, s19, 0
	global_load_dword v46, v4, s[18:19]
	s_add_u32 s18, s18, s21
; #define LAS __attribute__((address_space(3)))
; __device__ __forceinline__ unsigned pk2(float lo, float hi) { unsigned r; asm volatile("v_cvt_pk_bf16_f32 %0, %1, %2" : "=v"(r) : "v"(lo), "v"(hi)); return r; }
; __device__ __forceinline__ const float* argf(int i) { return (const float*)kargs()[i]; }
; __device__ __forceinline__ void transpose_tile(const float* src, int Nsrc, bf16_t* dst, int K, int n0, int k0, int mode, LAS float* scr, int tid) {
;     const int c = tid & 63, r0 = tid >> 6;
;     const int sc = colmap(mode, n0 + c);
; #pragma unroll
;     for (int i = 0; i < 8; ++i) { const int r = r0 + 8 * i; scr[r * 65 + c] = sc >= 0 ? src[(size_t)(k0 + r) * Nsrc + sc] : 0.f; }
;     __syncthreads();
;     const int kp = (tid & 31) * 2;
; #pragma unroll
;     for (int i = 0; i < 4; ++i) { const int r = (tid >> 5) + 16 * i;
;         *(unsigned*)(dst + (size_t)(n0 + r) * K + k0 + kp) = pk2(scr[kp * 65 + r], scr[(kp + 1) * 65 + r]); }
; __global__ void __launch_bounds__(512, 2) fwd_megakernel(Args a_unused) {
;     ...
;       for (int it = bid; it < 2 * I_L; it += G) {
;           const int l = it / I_L; int r = it % I_L;
;           if (r < I_IN) { transpose_tile(argf(5) + (size_t)l * D * INW, INW, (bf16_t*)(ws + WS_WIN) + (size_t)l * INP * D, D, (r / 16) * 64, (r % 16) * 64, 0, ldsf, tid); continue; } r -= I_IN;
;           if (r < I_OUT) { transpose_tile(argf(23) + (size_t)l * D * D, D, (bf16_t*)(ws + WS_WOUT) + (size_t)l * D * D, D, (r / 16) * 64, (r % 16) * 64, 1, ldsf, tid); continue; } r -= I_OUT;
;           if (r < I_UP) { transpose_tile(argf(26) + (size_t)l * D * NUP, NUP, (bf16_t*)(ws + WS_WUP) + (size_t)l * NUP * D, D, (r / 16) * 64, (r % 16) * 64, 2, ldsf, tid); continue; } r -= I_UP;
;           transpose_tile(argf(27) + (size_t)l * DFF * D, D, (bf16_t*)(ws + WS_WDN) + (size_t)l * D * DFF, DFF, (r / 44) * 64, (r % 44) * 64, 1, ldsf, tid);
	s_addc_u32 s19, s19, 0
	global_load_dword v47, v4, s[18:19]
	s_add_u32 s18, s18, s21
	s_addc_u32 s19, s19, 0
	global_load_dword v48, v4, s[18:19]
	s_add_u32 s18, s18, s21
	s_addc_u32 s19, s19, 0
	global_load_dword v49, v4, s[18:19]
	s_add_u32 s18, s18, s21
	s_addc_u32 s19, s19, 0
	global_load_dword v50, v4, s[18:19]
	s_add_u32 s18, s18, s21
	s_addc_u32 s19, s19, 0
	global_load_dword v51, v4, s[18:19]
	s_add_u32 s18, s18, s21
	s_addc_u32 s19, s19, 0
	global_load_dword v52, v4, s[18:19]
	s_add_u32 s18, s18, s21
	s_addc_u32 s19, s19, 0
	global_load_dword v53, v4, s[18:19]
	s_add_u32 s18, s18, s21
	s_addc_u32 s19, s19, 0
	global_load_dword v54, v4, s[18:19]
	s_add_u32 s18, s18, s21
	s_addc_u32 s19, s19, 0
	global_load_dword v55, v4, s[18:19]
	s_add_u32 s18, s18, s21
	s_addc_u32 s19, s19, 0
	global_load_dword v56, v4, s[18:19]
	s_add_u32 s18, s18, s21
	s_addc_u32 s19, s19, 0
	global_load_dword v57, v4, s[18:19]
	s_add_u32 s18, s18, s21
	s_addc_u32 s19, s19, 0
	global_load_dword v58, v4, s[18:19]
	s_add_u32 s18, s18, s21
	s_addc_u32 s19, s19, 0
	global_load_dword v59, v4, s[18:19]
	s_add_u32 s18, s18, s21
	s_addc_u32 s19, s19, 0
	global_load_dword v60, v4, s[18:19]
	s_add_u32 s18, s18, s21
	s_addc_u32 s19, s19, 0
	global_load_dword v61, v4, s[18:19]
	s_add_u32 s18, s18, s21
	s_addc_u32 s19, s19, 0
	global_load_dword v62, v4, s[18:19]
	s_add_u32 s18, s18, s21
	s_addc_u32 s19, s19, 0
	global_load_dword v63, v4, s[18:19]
	s_add_u32 s18, s18, s21
	s_addc_u32 s19, s19, 0
	global_load_dword v64, v4, s[18:19]
	s_add_u32 s18, s18, s21
	s_addc_u32 s19, s19, 0
	global_load_dword v65, v4, s[18:19]
	s_add_u32 s18, s18, s21
	s_addc_u32 s19, s19, 0
	global_load_dword v66, v4, s[18:19]
	s_add_u32 s18, s18, s21
	s_addc_u32 s19, s19, 0
	global_load_dword v67, v4, s[18:19]
	s_add_u32 s18, s18, s21
	s_addc_u32 s19, s19, 0
	global_load_dword v68, v4, s[18:19]
	s_add_u32 s18, s18, s21
	s_addc_u32 s19, s19, 0
	global_load_dword v69, v4, s[18:19]
	s_add_u32 s18, s18, s21
	s_addc_u32 s19, s19, 0
	global_load_dword v70, v4, s[18:19]
	s_add_u32 s18, s18, s21
	s_addc_u32 s19, s19, 0
	global_load_dword v71, v4, s[18:19]
	s_add_u32 s18, s18, s21
	s_addc_u32 s19, s19, 0
	global_load_dword v72, v4, s[18:19]
	s_add_u32 s18, s18, s21
	s_addc_u32 s19, s19, 0
	global_load_dword v73, v4, s[18:19]
	s_add_u32 s18, s18, s21
	s_addc_u32 s19, s19, 0
	s_waitcnt vmcnt(36)
	v_cvt_pk_bf16_f32 v10, v10, v11
	v_cvt_pk_bf16_f32 v11, v12, v13
	v_cvt_pk_bf16_f32 v12, v14, v15
	v_cvt_pk_bf16_f32 v13, v16, v17
	v_and_b32_e32 v10, v10, v9
	v_and_b32_e32 v11, v11, v9
	v_and_b32_e32 v12, v12, v9
	v_and_b32_e32 v13, v13, v9
	global_store_dwordx4 v3, v[10:13], s[14:15]
	v_cvt_pk_bf16_f32 v18, v18, v19
	v_cvt_pk_bf16_f32 v19, v20, v21
	v_cvt_pk_bf16_f32 v20, v22, v23
	v_cvt_pk_bf16_f32 v21, v24, v25
	v_and_b32_e32 v18, v18, v9
	v_and_b32_e32 v19, v19, v9
	v_and_b32_e32 v20, v20, v9
	v_and_b32_e32 v21, v21, v9
	global_store_dwordx4 v3, v[18:21], s[14:15] offset:16
	v_cvt_pk_bf16_f32 v26, v26, v27
	v_cvt_pk_bf16_f32 v27, v28, v29
	v_cvt_pk_bf16_f32 v28, v30, v31
	v_cvt_pk_bf16_f32 v29, v32, v33
	v_and_b32_e32 v26, v26, v9
	v_and_b32_e32 v27, v27, v9
	v_and_b32_e32 v28, v28, v9
	v_and_b32_e32 v29, v29, v9
	global_store_dwordx4 v3, v[26:29], s[14:15] offset:32
	v_cvt_pk_bf16_f32 v34, v34, v35
	v_cvt_pk_bf16_f32 v35, v36, v37
	v_cvt_pk_bf16_f32 v36, v38, v39
	v_cvt_pk_bf16_f32 v37, v40, v41
	v_and_b32_e32 v34, v34, v9
	v_and_b32_e32 v35, v35, v9
	v_and_b32_e32 v36, v36, v9
	v_and_b32_e32 v37, v37, v9
	global_store_dwordx4 v3, v[34:37], s[14:15] offset:48
	s_add_u32 s14, s14, 64
	s_addc_u32 s15, s15, 0
	s_waitcnt vmcnt(4)
	v_cvt_pk_bf16_f32 v42, v42, v43
	v_cvt_pk_bf16_f32 v43, v44, v45
	v_cvt_pk_bf16_f32 v44, v46, v47
	v_cvt_pk_bf16_f32 v45, v48, v49
	v_and_b32_e32 v42, v42, v9
	v_and_b32_e32 v43, v43, v9
	v_and_b32_e32 v44, v44, v9
	v_and_b32_e32 v45, v45, v9
	global_store_dwordx4 v3, v[42:45], s[14:15]
	v_cvt_pk_bf16_f32 v50, v50, v51
	v_cvt_pk_bf16_f32 v51, v52, v53
	v_cvt_pk_bf16_f32 v52, v54, v55
	v_cvt_pk_bf16_f32 v53, v56, v57
	v_and_b32_e32 v50, v50, v9
	v_and_b32_e32 v51, v51, v9
	v_and_b32_e32 v52, v52, v9
	v_and_b32_e32 v53, v53, v9
	global_store_dwordx4 v3, v[50:53], s[14:15] offset:16
	v_cvt_pk_bf16_f32 v58, v58, v59
	v_cvt_pk_bf16_f32 v59, v60, v61
	v_cvt_pk_bf16_f32 v60, v62, v63
	v_cvt_pk_bf16_f32 v61, v64, v65
	v_and_b32_e32 v58, v58, v9
	v_and_b32_e32 v59, v59, v9
	v_and_b32_e32 v60, v60, v9
	v_and_b32_e32 v61, v61, v9
	global_store_dwordx4 v3, v[58:61], s[14:15] offset:32
	v_cvt_pk_bf16_f32 v66, v66, v67
	v_cvt_pk_bf16_f32 v67, v68, v69
	v_cvt_pk_bf16_f32 v68, v70, v71
	v_cvt_pk_bf16_f32 v69, v72, v73
	v_and_b32_e32 v66, v66, v9
	v_and_b32_e32 v67, v67, v9
	v_and_b32_e32 v68, v68, v9
	v_and_b32_e32 v69, v69, v9
	global_store_dwordx4 v3, v[66:69], s[14:15] offset:48
	s_add_u32 s14, s14, 64
	s_addc_u32 s15, s15, 0
.Ltr_done:
	s_branch .LBB0_37
.Ltr_orig:
	s_cmpk_gt_i32 s2, 0x197f
	s_cbranch_scc1 .LBB0_37
	s_load_dwordx2 s[4:5], s[4:5], 0xf8
	v_and_b32_e32 v8, 63, v2
	v_lshlrev_b32_e32 v2, 1, v2
	v_ashrrev_i32_e32 v9, 6, v104
	s_movk_i32 s6, 0x104
	s_waitcnt lgkmcnt(0)
	s_add_u32 s16, s4, 0x2800000
	s_addc_u32 s17, s5, 0
	s_add_u32 s18, s4, 0x1200000
	v_and_b32_e32 v2, 62, v2
	v_ashrrev_i32_e32 v17, 5, v104
	s_addc_u32 s19, s5, 0
	v_lshl_add_u32 v4, v8, 2, 0
	v_mul_lo_u32 v5, v9, s6
	v_mul_u32_u24_e32 v6, 0x104, v2
	v_lshlrev_b32_e32 v7, 2, v17
	s_add_u32 s20, s4, 0xe00000
	v_add_u32_e32 v10, 8, v9
	v_add_u32_e32 v11, 16, v9
	v_add_u32_e32 v12, 24, v9
	v_add_u32_e32 v13, 32, v9
	v_add_u32_e32 v14, 40, v9
	v_add_u32_e32 v15, 48, v9
	v_add_u32_e32 v16, 56, v9
	v_mov_b32_e32 v3, 0
	v_add3_u32 v18, 0, v6, v7
	v_add_u32_e32 v19, 16, v17
	v_add_u32_e32 v20, 32, v17
	v_add_u32_e32 v21, 48, v17
	s_addc_u32 s21, s5, 0
	s_lshl_b32 s22, s2, 6
	s_lshl_b32 s23, s3, 6
	s_lshl_b32 s24, s2, 2
	s_lshl_b32 s25, s3, 2
	v_add_u32_e32 v22, v4, v5
	s_movk_i32 s26, 0x1600
	s_movk_i32 s27, 0x5800
	s_movk_i32 s28, 0xd14
	s_movk_i32 s29, 0x3450
	v_lshlrev_b32_e32 v4, 1, v2
	s_mov_b32 s30, s2
	s_branch .LBB0_10
